# v17 + de-serialized top-k select loops (8 independent SGPR ballot pairs per group instead of one vcc chain)
# speedup vs baseline: 1.0029x; 1.0029x over previous
.LBB0_654:
	v_lshlrev_b32_e64 v37, v36, 1
	v_or_b32_e32 v37, v37, v35
	v_cmp_ge_u32_e64 s[78:79], v5, v37
	v_cmp_ge_u32_e64 s[82:83], v4, v37
	v_cmp_ge_u32_e64 s[84:85], v7, v37
	v_cmp_ge_u32_e64 s[86:87], v6, v37
	v_cmp_ge_u32_e64 s[90:91], v9, v37
	v_cmp_ge_u32_e64 s[92:93], v8, v37
	v_cmp_ge_u32_e64 s[94:95], v11, v37
	v_cmp_ge_u32_e64 s[76:77], v10, v37
	s_bcnt1_i32_b64 s0, s[78:79]
	s_bcnt1_i32_b64 s1, s[82:83]
	s_add_i32 s0, s0, s1
	s_bcnt1_i32_b64 s1, s[84:85]
	s_add_i32 s0, s0, s1
	s_bcnt1_i32_b64 s1, s[86:87]
	s_add_i32 s0, s0, s1
	s_bcnt1_i32_b64 s1, s[90:91]
	s_add_i32 s0, s0, s1
	s_bcnt1_i32_b64 s1, s[92:93]
	s_add_i32 s0, s0, s1
	s_bcnt1_i32_b64 s1, s[94:95]
	s_add_i32 s0, s0, s1
	s_bcnt1_i32_b64 s1, s[76:77]
	s_add_i32 s0, s0, s1
	v_cmp_ge_u32_e64 s[78:79], v13, v37
	v_cmp_ge_u32_e64 s[82:83], v12, v37
	v_cmp_ge_u32_e64 s[84:85], v15, v37
	v_cmp_ge_u32_e64 s[86:87], v14, v37
	v_cmp_ge_u32_e64 s[90:91], v17, v37
	v_cmp_ge_u32_e64 s[92:93], v16, v37
	v_cmp_ge_u32_e64 s[94:95], v19, v37
	v_cmp_ge_u32_e64 s[76:77], v18, v37
	s_bcnt1_i32_b64 s1, s[78:79]
	s_add_i32 s0, s0, s1
	s_bcnt1_i32_b64 s1, s[82:83]
	s_add_i32 s0, s0, s1
	s_bcnt1_i32_b64 s1, s[84:85]
	s_add_i32 s0, s0, s1
	s_bcnt1_i32_b64 s1, s[86:87]
	s_add_i32 s0, s0, s1
	s_bcnt1_i32_b64 s1, s[90:91]
	s_add_i32 s0, s0, s1
	s_bcnt1_i32_b64 s1, s[92:93]
	s_add_i32 s0, s0, s1
	s_bcnt1_i32_b64 s1, s[94:95]
	s_add_i32 s0, s0, s1
	s_bcnt1_i32_b64 s1, s[76:77]
	s_add_i32 s0, s0, s1
	v_cmp_ge_u32_e64 s[78:79], v20, v37
	v_cmp_ge_u32_e64 s[82:83], v3, v37
	v_cmp_ge_u32_e64 s[84:85], v2, v37
	v_cmp_ge_u32_e64 s[86:87], v22, v37
	v_cmp_ge_u32_e64 s[90:91], v21, v37
	v_cmp_ge_u32_e64 s[92:93], v24, v37
	v_cmp_ge_u32_e64 s[94:95], v23, v37
	v_cmp_ge_u32_e64 s[76:77], v26, v37
	s_bcnt1_i32_b64 s1, s[78:79]
	s_add_i32 s0, s0, s1
	s_bcnt1_i32_b64 s1, s[82:83]
	s_add_i32 s0, s0, s1
	s_bcnt1_i32_b64 s1, s[84:85]
	s_add_i32 s0, s0, s1
	s_bcnt1_i32_b64 s1, s[86:87]
	s_add_i32 s0, s0, s1
	s_bcnt1_i32_b64 s1, s[90:91]
	s_add_i32 s0, s0, s1
	s_bcnt1_i32_b64 s1, s[92:93]
	s_add_i32 s0, s0, s1
	s_bcnt1_i32_b64 s1, s[94:95]
	s_add_i32 s0, s0, s1
	s_bcnt1_i32_b64 s1, s[76:77]
	s_add_i32 s0, s0, s1
	v_cmp_ge_u32_e64 s[78:79], v25, v37
	v_cmp_ge_u32_e64 s[82:83], v28, v37
	v_cmp_ge_u32_e64 s[84:85], v27, v37
	v_cmp_ge_u32_e64 s[86:87], v30, v37
	v_cmp_ge_u32_e64 s[90:91], v29, v37
	v_cmp_ge_u32_e64 s[92:93], v32, v37
	v_cmp_ge_u32_e64 s[94:95], v31, v37
	v_cmp_ge_u32_e64 s[76:77], v34, v37
	s_bcnt1_i32_b64 s1, s[78:79]
	s_add_i32 s0, s0, s1
	s_bcnt1_i32_b64 s1, s[82:83]
	s_add_i32 s0, s0, s1
	s_bcnt1_i32_b64 s1, s[84:85]
	s_add_i32 s0, s0, s1
	s_bcnt1_i32_b64 s1, s[86:87]
	s_add_i32 s0, s0, s1
	s_bcnt1_i32_b64 s1, s[90:91]
	s_add_i32 s0, s0, s1
	s_bcnt1_i32_b64 s1, s[92:93]
	s_add_i32 s0, s0, s1
	s_bcnt1_i32_b64 s1, s[94:95]
	s_add_i32 s0, s0, s1
	s_bcnt1_i32_b64 s1, s[76:77]
	s_add_i32 s0, s0, s1
	v_cmp_ge_u32_e64 s[78:79], v33, v37
	s_bcnt1_i32_b64 s1, s[78:79]
	s_add_i32 s0, s0, s1
	s_cmpk_gt_u32 s0, 0xff
	s_cselect_b64 vcc, -1, 0
	s_cmpk_eq_i32 s0, 0x100
	v_cndmask_b32_e32 v35, v35, v37, vcc
	s_cselect_b64 s[0:1], -1, 0
	v_subrev_co_u32_e32 v36, vcc, 1, v36
	s_or_b64 s[0:1], s[0:1], vcc
	s_andn2_b64 vcc, exec, s[0:1]
	s_cbranch_vccnz .LBB0_654
	v_cmp_ge_u32_e64 s[0:1], v3, v35
	v_cmp_ge_i32_e64 s[8:9], s59, v109
	s_and_b64 s[0:1], s[8:9], s[0:1]
	v_cmp_ge_u32_e64 s[8:9], v2, v35
	v_cmp_ge_i32_e64 s[10:11], s59, v110
	s_and_b64 s[8:9], s[10:11], s[8:9]
	v_cndmask_b32_e64 v2, 0, 1, s[8:9]
	v_cmp_ge_u32_e64 s[8:9], v22, v35
	v_cmp_ge_i32_e64 s[10:11], s59, v111
	s_and_b64 s[8:9], s[10:11], s[8:9]
	v_cmp_ne_u32_e64 s[78:79], 0, v2
	v_cndmask_b32_e64 v2, 0, 1, s[8:9]
	v_cmp_ge_u32_e64 s[8:9], v21, v35
	v_cmp_ge_i32_e64 s[10:11], s59, v112
	s_and_b64 s[8:9], s[10:11], s[8:9]
	v_cmp_ne_u32_e64 s[82:83], 0, v2
	v_cndmask_b32_e64 v2, 0, 1, s[8:9]
	v_cmp_ge_u32_e64 s[8:9], v24, v35
	v_cmp_ge_i32_e64 s[10:11], s59, v113
	s_and_b64 s[8:9], s[10:11], s[8:9]
	v_cmp_ne_u32_e64 s[84:85], 0, v2
	v_cndmask_b32_e64 v2, 0, 1, s[8:9]
	v_cmp_ge_u32_e64 s[8:9], v23, v35
	v_cmp_ge_i32_e64 s[10:11], s59, v114
	s_and_b64 s[8:9], s[10:11], s[8:9]
	v_cmp_ne_u32_e64 s[86:87], 0, v2
	v_cndmask_b32_e64 v2, 0, 1, s[8:9]
	v_cmp_ge_u32_e64 s[8:9], v26, v35
	v_cmp_ge_i32_e64 s[10:11], s59, v115
	s_and_b64 s[8:9], s[10:11], s[8:9]
	v_cmp_ne_u32_e64 s[90:91], 0, v2
	v_cndmask_b32_e64 v2, 0, 1, s[8:9]
	v_cmp_ge_u32_e64 s[8:9], v25, v35
	v_cmp_ge_i32_e64 s[10:11], s59, v116
	s_and_b64 s[8:9], s[10:11], s[8:9]
	v_cmp_ne_u32_e64 s[92:93], 0, v2
	v_cndmask_b32_e64 v2, 0, 1, s[8:9]
	v_cmp_ge_u32_e64 s[8:9], v28, v35
	v_cmp_ge_i32_e64 s[10:11], s59, v117
	s_and_b64 s[8:9], s[10:11], s[8:9]
	v_cmp_ne_u32_e64 s[94:95], 0, v2
	v_cndmask_b32_e64 v2, 0, 1, s[8:9]
	v_cmp_ge_u32_e64 s[8:9], v27, v35
	v_cmp_ge_i32_e64 s[10:11], s59, v118
	s_and_b64 s[8:9], s[10:11], s[8:9]
	v_cmp_ge_u32_e64 s[10:11], v30, v35
	v_cmp_ge_i32_e64 s[12:13], s59, v119
	v_cmp_ne_u32_e64 s[76:77], 0, v2
	v_cndmask_b32_e64 v2, 0, 1, s[8:9]
	s_and_b64 s[10:11], s[12:13], s[10:11]
	v_cmp_ge_u32_e64 s[12:13], v29, v35
	v_cmp_ge_i32_e64 s[16:17], s59, v120
	v_cmp_ne_u32_e64 s[8:9], 0, v2
	v_cndmask_b32_e64 v2, 0, 1, s[10:11]
	s_and_b64 s[12:13], s[16:17], s[12:13]
	v_cmp_ge_u32_e64 s[16:17], v32, v35
	v_cmp_ge_i32_e64 s[18:19], s59, v121
	v_cmp_ne_u32_e64 s[10:11], 0, v2
	v_cndmask_b32_e64 v2, 0, 1, s[12:13]
	s_and_b64 s[16:17], s[18:19], s[16:17]
	v_cmp_ge_u32_e64 s[18:19], v31, v35
	v_cmp_ge_i32_e64 s[20:21], s59, v122
	v_cmp_ne_u32_e64 s[12:13], 0, v2
	v_cndmask_b32_e64 v2, 0, 1, s[16:17]
	s_and_b64 s[18:19], s[20:21], s[18:19]
	v_cmp_ge_u32_e64 s[20:21], v34, v35
	v_cmp_ge_i32_e64 s[24:25], s59, v123
	v_cmp_ne_u32_e64 s[16:17], 0, v2
	v_cndmask_b32_e64 v2, 0, 1, s[18:19]
	s_and_b64 s[20:21], s[24:25], s[20:21]
	v_cmp_ge_u32_e64 s[24:25], v33, v35
	v_cmp_ge_i32_e32 vcc, s59, v124
	v_cmp_ne_u32_e64 s[18:19], 0, v2
	v_cndmask_b32_e64 v2, 0, 1, s[20:21]
	s_and_b64 s[24:25], vcc, s[24:25]
	v_cndmask_b32_e64 v3, 0, 1, s[0:1]
	v_cmp_ne_u32_e64 s[20:21], 0, v2
	v_cndmask_b32_e64 v2, 0, 1, s[24:25]
	v_cmp_ge_u32_e64 s[48:49], v5, v35
	v_cmp_ge_u32_e64 s[44:45], v4, v35
	v_cmp_ge_u32_e64 s[42:43], v7, v35
	v_cmp_ge_u32_e64 s[6:7], v6, v35
	v_cmp_ge_u32_e64 s[40:41], v9, v35
	v_cmp_ge_u32_e64 s[38:39], v8, v35
	v_cmp_ge_u32_e64 s[36:37], v11, v35
	v_cmp_ge_u32_e64 s[34:35], v10, v35
	v_cmp_ge_u32_e64 s[30:31], v13, v35
	v_cmp_ge_u32_e64 s[28:29], v12, v35
	v_cmp_ge_u32_e64 s[26:27], v15, v35
	v_cmp_ge_u32_e64 s[22:23], v14, v35
	v_cmp_ge_u32_e64 s[14:15], v17, v35
	v_cmp_ge_u32_e64 s[96:97], v16, v35
	v_cmp_ge_u32_e64 s[88:89], v19, v35
	v_cmp_ge_u32_e64 s[80:81], v18, v35
	v_cmp_ge_u32_e64 s[46:47], v20, v35
	v_cmp_ne_u32_e64 s[0:1], 0, v3
	v_cmp_ne_u32_e64 s[24:25], 0, v2
	s_mov_b64 vcc, 0
	s_mov_b64 s[66:67], 0
	s_mov_b64 s[68:69], exec
	v_readlane_b32 s74, v251, 19
	v_readlane_b32 s75, v251, 20
	s_and_b64 s[74:75], s[68:69], s[74:75]
	s_xor_b64 s[68:69], s[74:75], s[68:69]
	s_mov_b64 exec, s[74:75]
	s_cbranch_execz .LBB0_657
	v_readlane_b32 s66, v250, 21
	v_mov_b32_e32 v2, s49
	v_readlane_b32 s67, v250, 22
	v_mov_b32_e32 v3, s48
	v_readlane_b32 s48, v250, 19
	v_cndmask_b32_e64 v3, 0, v3, s[66:67]
	v_mov_b32_e32 v21, s44
	v_readlane_b32 s49, v250, 20
	v_cndmask_b32_e64 v2, 0, v2, s[66:67]
	s_mov_b64 s[66:67], exec
	v_cndmask_b32_e64 v3, v3, v21, s[48:49]
	v_mov_b32_e32 v21, s45
	v_readlane_b32 s44, v250, 17
	v_cndmask_b32_e64 v2, v2, v21, s[48:49]
	v_mov_b32_e32 v21, s43
	v_readlane_b32 s45, v250, 18
	s_nop 1
	v_cndmask_b32_e64 v2, v2, v21, s[44:45]
	v_mov_b32_e32 v21, s42
	v_readlane_b32 s42, v250, 15
	v_cndmask_b32_e64 v3, v3, v21, s[44:45]
	v_mov_b32_e32 v21, s6
	v_readlane_b32 s43, v250, 16
	s_nop 1
	v_cndmask_b32_e64 v3, v3, v21, s[42:43]
	v_mov_b32_e32 v21, s7
	v_readlane_b32 s6, v250, 13
	v_cndmask_b32_e64 v2, v2, v21, s[42:43]
	v_mov_b32_e32 v21, s41
	v_readlane_b32 s7, v250, 14
	s_nop 1
	v_cndmask_b32_e64 v2, v2, v21, s[6:7]
	v_mov_b32_e32 v21, s40
	v_cndmask_b32_e64 v3, v3, v21, s[6:7]
	v_readlane_b32 s6, v250, 11
	v_mov_b32_e32 v21, s38
	v_readlane_b32 s7, v250, 12
	s_nop 1
	v_cndmask_b32_e64 v3, v3, v21, s[6:7]
	v_mov_b32_e32 v21, s39
	v_cndmask_b32_e64 v2, v2, v21, s[6:7]
	v_readlane_b32 s6, v250, 9
	v_mov_b32_e32 v21, s37
	v_readlane_b32 s7, v250, 10
	s_nop 1
	v_cndmask_b32_e64 v2, v2, v21, s[6:7]
	v_mov_b32_e32 v21, s36
	v_cndmask_b32_e64 v3, v3, v21, s[6:7]
	v_readlane_b32 s6, v250, 7
	v_mov_b32_e32 v21, s34
	v_readlane_b32 s7, v250, 8
	s_nop 1
	v_cndmask_b32_e64 v3, v3, v21, s[6:7]
	v_mov_b32_e32 v21, s35
	v_cndmask_b32_e64 v2, v2, v21, s[6:7]
	v_readlane_b32 s6, v250, 5
	v_mov_b32_e32 v21, s31
	v_readlane_b32 s7, v250, 6
	s_nop 1
	v_cndmask_b32_e64 v2, v2, v21, s[6:7]
	v_mov_b32_e32 v21, s30
	v_cndmask_b32_e64 v3, v3, v21, s[6:7]
	v_readlane_b32 s6, v250, 3
	v_mov_b32_e32 v21, s28
	v_readlane_b32 s7, v250, 4
	s_nop 1
	v_cndmask_b32_e64 v3, v3, v21, s[6:7]
	v_mov_b32_e32 v21, s29
	v_cndmask_b32_e64 v2, v2, v21, s[6:7]
	v_readlane_b32 s6, v250, 1
	v_mov_b32_e32 v21, s27
	v_readlane_b32 s7, v250, 2
	s_nop 1
	v_cndmask_b32_e64 v2, v2, v21, s[6:7]
	v_mov_b32_e32 v21, s26
	v_cndmask_b32_e64 v3, v3, v21, s[6:7]
	v_readlane_b32 s6, v251, 63
	v_mov_b32_e32 v21, s22
	v_readlane_b32 s7, v250, 0
	s_nop 1
	v_cndmask_b32_e64 v3, v3, v21, s[6:7]
	v_mov_b32_e32 v21, s23
	v_cndmask_b32_e64 v2, v2, v21, s[6:7]
	v_readlane_b32 s6, v251, 61
	v_mov_b32_e32 v21, s15
	v_readlane_b32 s7, v251, 62
	s_nop 1
	v_cndmask_b32_e64 v2, v2, v21, s[6:7]
	v_mov_b32_e32 v21, s14
	v_cndmask_b32_e64 v3, v3, v21, s[6:7]
	v_readlane_b32 s6, v251, 59
	v_mov_b32_e32 v21, s96
	v_readlane_b32 s7, v251, 60
	s_nop 1
	v_cndmask_b32_e64 v3, v3, v21, s[6:7]
	v_mov_b32_e32 v21, s97
	v_cndmask_b32_e64 v2, v2, v21, s[6:7]
	v_readlane_b32 s6, v251, 57
	v_mov_b32_e32 v21, s89
	v_readlane_b32 s7, v251, 58
	s_nop 1
	v_cndmask_b32_e64 v2, v2, v21, s[6:7]
	v_mov_b32_e32 v21, s88
	v_cndmask_b32_e64 v3, v3, v21, s[6:7]
	v_readlane_b32 s6, v251, 55
	v_mov_b32_e32 v21, s80
	v_readlane_b32 s7, v251, 56
	s_nop 1
	v_cndmask_b32_e64 v3, v3, v21, s[6:7]
	v_mov_b32_e32 v21, s81
	v_cndmask_b32_e64 v2, v2, v21, s[6:7]
	v_readlane_b32 s6, v251, 53
	v_mov_b32_e32 v21, s47
	v_readlane_b32 s7, v251, 54
	s_nop 1
	v_cndmask_b32_e64 v2, v2, v21, s[6:7]
	v_mov_b32_e32 v21, s46
	v_cndmask_b32_e64 v3, v3, v21, s[6:7]
	v_readlane_b32 s6, v251, 51
	v_mov_b32_e32 v21, s0
	v_readlane_b32 s7, v251, 52
	s_nop 1
	v_cndmask_b32_e64 v3, v3, v21, s[6:7]
	v_mov_b32_e32 v21, s1
	v_readlane_b32 s0, v251, 49
	v_cndmask_b32_e64 v2, v2, v21, s[6:7]
	v_mov_b32_e32 v21, s79
	v_readlane_b32 s1, v251, 50
	s_nop 1
	v_cndmask_b32_e64 v2, v2, v21, s[0:1]
	v_mov_b32_e32 v21, s78
	v_cndmask_b32_e64 v3, v3, v21, s[0:1]
	v_readlane_b32 s0, v251, 47
	v_mov_b32_e32 v21, s82
	v_readlane_b32 s1, v251, 48
	s_nop 1
	v_cndmask_b32_e64 v3, v3, v21, s[0:1]
	v_mov_b32_e32 v21, s83
	v_cndmask_b32_e64 v2, v2, v21, s[0:1]
	v_readlane_b32 s0, v251, 45
	v_mov_b32_e32 v21, s85
	v_readlane_b32 s1, v251, 46
	s_nop 1
	v_cndmask_b32_e64 v2, v2, v21, s[0:1]
	v_mov_b32_e32 v21, s84
	v_cndmask_b32_e64 v3, v3, v21, s[0:1]
	v_readlane_b32 s0, v251, 43
	v_mov_b32_e32 v21, s86
	v_readlane_b32 s1, v251, 44
	s_nop 1
	v_cndmask_b32_e64 v3, v3, v21, s[0:1]
	v_mov_b32_e32 v21, s87
	v_cndmask_b32_e64 v2, v2, v21, s[0:1]
	v_readlane_b32 s0, v251, 41
	v_mov_b32_e32 v21, s91
	v_readlane_b32 s1, v251, 42
	s_nop 1
	v_cndmask_b32_e64 v2, v2, v21, s[0:1]
	v_mov_b32_e32 v21, s90
	v_cndmask_b32_e64 v3, v3, v21, s[0:1]
	v_readlane_b32 s0, v251, 39
	v_mov_b32_e32 v21, s92
	v_readlane_b32 s1, v251, 40
	s_nop 1
	v_cndmask_b32_e64 v3, v3, v21, s[0:1]
	v_mov_b32_e32 v21, s93
	v_cndmask_b32_e64 v2, v2, v21, s[0:1]
	v_readlane_b32 s0, v251, 37
	v_mov_b32_e32 v21, s95
	v_readlane_b32 s1, v251, 38
	s_nop 1
	v_cndmask_b32_e64 v2, v2, v21, s[0:1]
	v_mov_b32_e32 v21, s94
	v_cndmask_b32_e64 v3, v3, v21, s[0:1]
	v_readlane_b32 s0, v251, 35
	v_mov_b32_e32 v21, s76
	v_readlane_b32 s1, v251, 36
	s_nop 1
	v_cndmask_b32_e64 v3, v3, v21, s[0:1]
	v_mov_b32_e32 v21, s77
	v_cndmask_b32_e64 v2, v2, v21, s[0:1]
	v_readlane_b32 s0, v251, 33
	v_mov_b32_e32 v21, s9
	v_readlane_b32 s1, v251, 34
	s_nop 1
	v_cndmask_b32_e64 v2, v2, v21, s[0:1]
	v_mov_b32_e32 v21, s8
	v_cndmask_b32_e64 v3, v3, v21, s[0:1]
	v_readlane_b32 s0, v251, 31
	v_mov_b32_e32 v21, s10
	v_readlane_b32 s1, v251, 32
	s_nop 1
	v_cndmask_b32_e64 v3, v3, v21, s[0:1]
	v_mov_b32_e32 v21, s11
	v_cndmask_b32_e64 v2, v2, v21, s[0:1]
	v_readlane_b32 s0, v251, 29
	v_mov_b32_e32 v21, s13
	v_readlane_b32 s1, v251, 30
	s_nop 1
	v_cndmask_b32_e64 v2, v2, v21, s[0:1]
	v_mov_b32_e32 v21, s12
	v_cndmask_b32_e64 v3, v3, v21, s[0:1]
	v_readlane_b32 s0, v251, 27
	v_mov_b32_e32 v21, s16
	v_readlane_b32 s1, v251, 28
	s_nop 1
	v_cndmask_b32_e64 v3, v3, v21, s[0:1]
	v_mov_b32_e32 v21, s17
	v_cndmask_b32_e64 v2, v2, v21, s[0:1]
	v_readlane_b32 s0, v251, 25
	v_mov_b32_e32 v21, s19
	v_readlane_b32 s1, v251, 26
	s_nop 1
	v_cndmask_b32_e64 v2, v2, v21, s[0:1]
	v_mov_b32_e32 v21, s18
	v_cndmask_b32_e64 v3, v3, v21, s[0:1]
	v_readlane_b32 s0, v251, 23
	v_mov_b32_e32 v21, s20
	v_readlane_b32 s1, v251, 24
	s_nop 1
	v_cndmask_b32_e64 v21, v3, v21, s[0:1]
	v_mov_b32_e32 v3, s21
	v_cndmask_b32_e64 v2, v2, v3, s[0:1]
	v_readlane_b32 s0, v251, 21
	v_mov_b32_e32 v3, s25
	v_readlane_b32 s1, v251, 22
	s_nop 1
	v_cndmask_b32_e64 v3, v2, v3, s[0:1]
	v_mov_b32_e32 v2, s24
	v_cndmask_b32_e64 v2, v21, v2, s[0:1]

.LBB0_662:
	v_lshlrev_b32_e64 v21, v3, 1
	v_or_b32_e32 v21, v21, v2
	v_cmp_ge_u32_e64 s[8:9], v5, v21
	v_cmp_ge_u32_e64 s[10:11], v4, v21
	v_cmp_ge_u32_e64 s[12:13], v7, v21
	v_cmp_ge_u32_e64 s[14:15], v6, v21
	v_cmp_ge_u32_e64 s[16:17], v9, v21
	v_cmp_ge_u32_e64 s[18:19], v8, v21
	v_cmp_ge_u32_e64 s[20:21], v11, v21
	v_cmp_ge_u32_e64 s[22:23], v10, v21
	s_bcnt1_i32_b64 s0, s[8:9]
	s_bcnt1_i32_b64 s1, s[10:11]
	s_add_i32 s0, s0, s1
	s_bcnt1_i32_b64 s1, s[12:13]
	s_add_i32 s0, s0, s1
	s_bcnt1_i32_b64 s1, s[14:15]
	s_add_i32 s0, s0, s1
	s_bcnt1_i32_b64 s1, s[16:17]
	s_add_i32 s0, s0, s1
	s_bcnt1_i32_b64 s1, s[18:19]
	s_add_i32 s0, s0, s1
	s_bcnt1_i32_b64 s1, s[20:21]
	s_add_i32 s0, s0, s1
	s_bcnt1_i32_b64 s1, s[22:23]
	s_add_i32 s0, s0, s1
	v_cmp_ge_u32_e64 s[8:9], v13, v21
	v_cmp_ge_u32_e64 s[10:11], v12, v21
	v_cmp_ge_u32_e64 s[12:13], v15, v21
	v_cmp_ge_u32_e64 s[14:15], v14, v21
	v_cmp_ge_u32_e64 s[16:17], v17, v21
	v_cmp_ge_u32_e64 s[18:19], v16, v21
	v_cmp_ge_u32_e64 s[20:21], v19, v21
	v_cmp_ge_u32_e64 s[22:23], v18, v21
	s_bcnt1_i32_b64 s1, s[8:9]
	s_add_i32 s0, s0, s1
	s_bcnt1_i32_b64 s1, s[10:11]
	s_add_i32 s0, s0, s1
	s_bcnt1_i32_b64 s1, s[12:13]
	s_add_i32 s0, s0, s1
	s_bcnt1_i32_b64 s1, s[14:15]
	s_add_i32 s0, s0, s1
	s_bcnt1_i32_b64 s1, s[16:17]
	s_add_i32 s0, s0, s1
	s_bcnt1_i32_b64 s1, s[18:19]
	s_add_i32 s0, s0, s1
	s_bcnt1_i32_b64 s1, s[20:21]
	s_add_i32 s0, s0, s1
	s_bcnt1_i32_b64 s1, s[22:23]
	s_add_i32 s0, s0, s1
	v_cmp_ge_u32_e64 s[8:9], v20, v21
	s_bcnt1_i32_b64 s1, s[8:9]
	s_add_i32 s0, s0, s1
	s_cmpk_gt_u32 s0, 0xff
	s_cselect_b64 vcc, -1, 0
	s_cmpk_eq_i32 s0, 0x100
	v_cndmask_b32_e32 v2, v2, v21, vcc
	s_cselect_b64 s[0:1], -1, 0
	v_subrev_co_u32_e32 v3, vcc, 1, v3
	s_or_b64 s[0:1], s[0:1], vcc
	s_andn2_b64 vcc, exec, s[0:1]
	s_cbranch_vccnz .LBB0_662
